# post_rwkv phase: hand-written row loop, all loads of a row issued together, next row prefetched under the math
# speedup vs baseline: 1.0101x; 1.0101x over previous
; DI float red16(float v) { v += DPPF(v, 0xB1); v += DPPF(v, 0x4E); v += DPPF(v, 0x141); v += DPPF(v, 0x140); return v; }
; DI f32x4 bf4_to_f4(u32x2 w) { return (f32x4){__uint_as_float(w.x << 16), __uint_as_float(w.x & 0xffff0000u), __uint_as_float(w.y << 16), __uint_as_float(w.y & 0xffff0000u)}; }
; DI void post_rwkv_phase(const PZ& p, int wave, int lane) {
;     ...
;     for (int m = gw; m < MTOK; m += NGW) {
;         f32x4 outv[4];
; #pragma unroll
;         for (int j = 0; j < 4; ++j) {
;             const int head = j * 4 + (lane >> 4);
;             const f32x4 y = bf4_to_f4(__builtin_nontemporal_load((const u32x2*)(HA + (size_t)m * 1024) + lane + 64 * j)) + bf4_to_f4(__builtin_nontemporal_load((const u32x2*)(YB + (size_t)m * 1024) + lane + 64 * j));
;             const float mu = red16(y.x + y.y + y.z + y.w) * (1.f / 64.f);
;             const f32x4 d = y - mu;
;             const float var = red16(d.x * d.x + d.y * d.y + d.z * d.z + d.w * d.w) * (1.f / 64.f);
;             const float rstd = rsqrtf(var + 64e-5f);
;             const f32x4 lw = *((const f32x4*)p.in(34) + lane + 64 * j), lb = *((const f32x4*)p.in(35) + lane + 64 * j);
;             const float bon = 0.5f * (BS[(size_t)m * 16 + head] + BS[((size_t)MTOK + m) * 16 + head]);
;             const f32x4 v = bf4_to_f4(__builtin_nontemporal_load((const u32x2*)(rkv + (size_t)m * 3072 + 2048) + lane + 64 * j));
;             const f32x4 gg = bf4_to_f4(__builtin_nontemporal_load((const u32x2*)(rkv + (size_t)m * 3072) + lane + 64 * j));
.Lprw_pre:
	global_load_dwordx4 v[70:73], v[0:1], off offset:0
	global_load_dwordx4 v[86:89], v[12:13], off offset:0
	global_load_dwordx4 v[74:77], v[0:1], off offset:1024
	global_load_dwordx4 v[90:93], v[12:13], off offset:1024
	global_load_dwordx4 v[78:81], v[0:1], off offset:2048
	global_load_dwordx4 v[94:97], v[12:13], off offset:2048
	global_load_dwordx4 v[82:85], v[0:1], off offset:3072
	global_load_dwordx4 v[98:101], v[12:13], off offset:3072
	v_mov_b32_e32 v107, 0x3c800000
	s_mov_b32 s5, 0
	v_lshl_add_u64 v[16:17], v[16:17], 0, s[86:87]
	v_lshl_add_u64 v[14:15], v[14:15], 0, s[86:87]
	v_lshl_add_u64 v[18:19], v[18:19], 0, s[86:87]
	s_mov_b32 s4, 0x9100000
	v_lshl_add_u64 v[4:5], v[16:17], 0, s[4:5]
	s_mov_b32 s4, 0x12100000
	v_lshl_add_u64 v[6:7], v[16:17], 0, s[4:5]
	s_mov_b32 s4, 0x1b101000
	v_lshl_add_u64 v[8:9], v[14:15], 0, s[4:5]
	s_mov_b32 s4, 0x1b100000
	v_lshl_add_u64 v[10:11], v[14:15], 0, s[4:5]
	s_mov_b32 s4, 0x3a900000
	v_lshl_add_u64 v[102:103], v[18:19], 0, s[4:5]
	s_mov_b32 s4, 0x3ad80000
	v_lshl_add_u64 v[104:105], v[18:19], 0, s[4:5]
	global_load_dwordx2 v[20:21], v[4:5], off offset:0 nt
	global_load_dwordx2 v[28:29], v[6:7], off offset:0 nt
	global_load_dwordx2 v[22:23], v[4:5], off offset:512 nt
	global_load_dwordx2 v[30:31], v[6:7], off offset:512 nt
	global_load_dwordx2 v[24:25], v[4:5], off offset:1024 nt
	global_load_dwordx2 v[32:33], v[6:7], off offset:1024 nt
	global_load_dwordx2 v[26:27], v[4:5], off offset:1536 nt
	global_load_dwordx2 v[34:35], v[6:7], off offset:1536 nt
	global_load_dword v52, v[102:103], off offset:0
	global_load_dword v56, v[104:105], off offset:0
	global_load_dword v53, v[102:103], off offset:16
	global_load_dword v57, v[104:105], off offset:16
	global_load_dword v54, v[102:103], off offset:32
	global_load_dword v58, v[104:105], off offset:32
	global_load_dword v55, v[102:103], off offset:48
	global_load_dword v59, v[104:105], off offset:48
	global_load_dwordx2 v[36:37], v[8:9], off offset:0 nt
	global_load_dwordx2 v[44:45], v[10:11], off offset:0 nt
	global_load_dwordx2 v[38:39], v[8:9], off offset:512 nt
	global_load_dwordx2 v[46:47], v[10:11], off offset:512 nt
	global_load_dwordx2 v[40:41], v[8:9], off offset:1024 nt
	global_load_dwordx2 v[48:49], v[10:11], off offset:1024 nt
	global_load_dwordx2 v[42:43], v[8:9], off offset:1536 nt
	global_load_dwordx2 v[50:51], v[10:11], off offset:1536 nt
	s_waitcnt vmcnt(0)
	s_branch .Lprw_body

; DI float red16(float v) { v += DPPF(v, 0xB1); v += DPPF(v, 0x4E); v += DPPF(v, 0x141); v += DPPF(v, 0x140); return v; }
; DI f32x4 bf4_to_f4(u32x2 w) { return (f32x4){__uint_as_float(w.x << 16), __uint_as_float(w.x & 0xffff0000u), __uint_as_float(w.y << 16), __uint_as_float(w.y & 0xffff0000u)}; }
; DI void post_rwkv_phase(const PZ& p, int wave, int lane) {
;     ...
;         for (int j = 0; j < 4; ++j) {
;             const int head = j * 4 + (lane >> 4);
;             const f32x4 y = bf4_to_f4(__builtin_nontemporal_load((const u32x2*)(HA + (size_t)m * 1024) + lane + 64 * j)) + bf4_to_f4(__builtin_nontemporal_load((const u32x2*)(YB + (size_t)m * 1024) + lane + 64 * j));
;             const float mu = red16(y.x + y.y + y.z + y.w) * (1.f / 64.f);
;             const f32x4 d = y - mu;
;             const float var = red16(d.x * d.x + d.y * d.y + d.z * d.z + d.w * d.w) * (1.f / 64.f);
;             const float rstd = rsqrtf(var + 64e-5f);
;             const f32x4 lw = *((const f32x4*)p.in(34) + lane + 64 * j), lb = *((const f32x4*)p.in(35) + lane + 64 * j);
;             const float bon = 0.5f * (BS[(size_t)m * 16 + head] + BS[((size_t)MTOK + m) * 16 + head]);
;             const f32x4 v = bf4_to_f4(__builtin_nontemporal_load((const u32x2*)(rkv + (size_t)m * 3072 + 2048) + lane + 64 * j));
;             const f32x4 gg = bf4_to_f4(__builtin_nontemporal_load((const u32x2*)(rkv + (size_t)m * 3072) + lane + 64 * j));
.Lprw_body:
	v_lshlrev_b32_e32 v216, 16, v20
	v_and_b32_e32 v217, 0xffff0000, v20
	v_lshlrev_b32_e32 v218, 16, v21
	v_and_b32_e32 v219, 0xffff0000, v21
	v_lshlrev_b32_e32 v220, 16, v28
	v_and_b32_e32 v221, 0xffff0000, v28
	v_lshlrev_b32_e32 v222, 16, v29
	v_and_b32_e32 v223, 0xffff0000, v29
	v_add_f32_e32 v110, v216, v220
	v_add_f32_e32 v111, v217, v221
	v_add_f32_e32 v112, v218, v222
	v_add_f32_e32 v113, v219, v223
	v_lshlrev_b32_e32 v126, 16, v36
	v_and_b32_e32 v127, 0xffff0000, v36
	v_lshlrev_b32_e32 v128, 16, v37
	v_and_b32_e32 v129, 0xffff0000, v37
	v_lshlrev_b32_e32 v169, 16, v44
	v_and_b32_e32 v170, 0xffff0000, v44
	v_lshlrev_b32_e32 v171, 16, v45
	v_and_b32_e32 v172, 0xffff0000, v45
	v_add_f32_e32 v185, v52, v56
	v_lshlrev_b32_e32 v216, 16, v22
	v_and_b32_e32 v217, 0xffff0000, v22
	v_lshlrev_b32_e32 v218, 16, v23
	v_and_b32_e32 v219, 0xffff0000, v23
	v_lshlrev_b32_e32 v220, 16, v30
	v_and_b32_e32 v221, 0xffff0000, v30
	v_lshlrev_b32_e32 v222, 16, v31
	v_and_b32_e32 v223, 0xffff0000, v31
	v_add_f32_e32 v114, v216, v220
	v_add_f32_e32 v115, v217, v221
	v_add_f32_e32 v116, v218, v222
	v_add_f32_e32 v117, v219, v223
	v_lshlrev_b32_e32 v130, 16, v38
	v_and_b32_e32 v131, 0xffff0000, v38
	v_lshlrev_b32_e32 v132, 16, v39
	v_and_b32_e32 v133, 0xffff0000, v39
	v_lshlrev_b32_e32 v173, 16, v46
	v_and_b32_e32 v174, 0xffff0000, v46
	v_lshlrev_b32_e32 v175, 16, v47
	v_and_b32_e32 v176, 0xffff0000, v47
	v_add_f32_e32 v186, v53, v57
	v_lshlrev_b32_e32 v216, 16, v24
	v_and_b32_e32 v217, 0xffff0000, v24
	v_lshlrev_b32_e32 v218, 16, v25
	v_and_b32_e32 v219, 0xffff0000, v25
	v_lshlrev_b32_e32 v220, 16, v32
	v_and_b32_e32 v221, 0xffff0000, v32
	v_lshlrev_b32_e32 v222, 16, v33
	v_and_b32_e32 v223, 0xffff0000, v33
	v_add_f32_e32 v118, v216, v220
	v_add_f32_e32 v119, v217, v221
	v_add_f32_e32 v120, v218, v222
	v_add_f32_e32 v121, v219, v223
	v_lshlrev_b32_e32 v134, 16, v40
	v_and_b32_e32 v135, 0xffff0000, v40
	v_lshlrev_b32_e32 v136, 16, v41
	v_and_b32_e32 v137, 0xffff0000, v41
	v_lshlrev_b32_e32 v177, 16, v48
	v_and_b32_e32 v178, 0xffff0000, v48
	v_lshlrev_b32_e32 v179, 16, v49
	v_and_b32_e32 v180, 0xffff0000, v49
	v_add_f32_e32 v187, v54, v58
	v_lshlrev_b32_e32 v216, 16, v26
	v_and_b32_e32 v217, 0xffff0000, v26
	v_lshlrev_b32_e32 v218, 16, v27
	v_and_b32_e32 v219, 0xffff0000, v27
	v_lshlrev_b32_e32 v220, 16, v34
	v_and_b32_e32 v221, 0xffff0000, v34
	v_lshlrev_b32_e32 v222, 16, v35
	v_and_b32_e32 v223, 0xffff0000, v35
	v_add_f32_e32 v122, v216, v220
	v_add_f32_e32 v123, v217, v221
	v_add_f32_e32 v124, v218, v222
	v_add_f32_e32 v125, v219, v223
	v_lshlrev_b32_e32 v138, 16, v42
	v_and_b32_e32 v139, 0xffff0000, v42
	v_lshlrev_b32_e32 v140, 16, v43
	v_and_b32_e32 v141, 0xffff0000, v43
	v_lshlrev_b32_e32 v181, 16, v50
	v_and_b32_e32 v182, 0xffff0000, v50
	v_lshlrev_b32_e32 v183, 16, v51
	v_and_b32_e32 v184, 0xffff0000, v51
	v_add_f32_e32 v188, v55, v59
	v_mul_f32_e32 v185, 0.5, v185
	v_mul_f32_e32 v186, 0.5, v186
	v_mul_f32_e32 v187, 0.5, v187
	v_mul_f32_e32 v188, 0.5, v188
	v_mov_b32_e32 v60, v4
	v_mov_b32_e32 v61, v5
	s_add_i32 s16, s16, s92
	v_lshl_add_u64 v[4:5], v[4:5], 0, s[14:15]
	v_lshl_add_u64 v[6:7], v[6:7], 0, s[14:15]
	v_lshl_add_u64 v[8:9], v[8:9], 0, s[6:7]
	v_lshl_add_u64 v[10:11], v[10:11], 0, s[6:7]
	v_lshl_add_u64 v[102:103], v[102:103], 0, s[8:9]
	v_lshl_add_u64 v[104:105], v[104:105], 0, s[8:9]
	s_cmp_gt_i32 s16, 0x11fff
	s_cbranch_scc1 .Lprw_nopf
	global_load_dwordx2 v[20:21], v[4:5], off offset:0 nt
	global_load_dwordx2 v[28:29], v[6:7], off offset:0 nt
	global_load_dwordx2 v[22:23], v[4:5], off offset:512 nt
	global_load_dwordx2 v[30:31], v[6:7], off offset:512 nt
	global_load_dwordx2 v[24:25], v[4:5], off offset:1024 nt
	global_load_dwordx2 v[32:33], v[6:7], off offset:1024 nt
	global_load_dwordx2 v[26:27], v[4:5], off offset:1536 nt
	global_load_dwordx2 v[34:35], v[6:7], off offset:1536 nt
	global_load_dword v52, v[102:103], off offset:0
	global_load_dword v56, v[104:105], off offset:0
	global_load_dword v53, v[102:103], off offset:16
	global_load_dword v57, v[104:105], off offset:16
	global_load_dword v54, v[102:103], off offset:32
	global_load_dword v58, v[104:105], off offset:32
	global_load_dword v55, v[102:103], off offset:48
	global_load_dword v59, v[104:105], off offset:48
	global_load_dwordx2 v[36:37], v[8:9], off offset:0 nt
	global_load_dwordx2 v[44:45], v[10:11], off offset:0 nt
	global_load_dwordx2 v[38:39], v[8:9], off offset:512 nt
	global_load_dwordx2 v[46:47], v[10:11], off offset:512 nt
	global_load_dwordx2 v[40:41], v[8:9], off offset:1024 nt
	global_load_dwordx2 v[48:49], v[10:11], off offset:1024 nt
	global_load_dwordx2 v[42:43], v[8:9], off offset:1536 nt
	global_load_dwordx2 v[50:51], v[10:11], off offset:1536 nt
; DI float red16(float v) { v += DPPF(v, 0xB1); v += DPPF(v, 0x4E); v += DPPF(v, 0x141); v += DPPF(v, 0x140); return v; }
; DI f32x4 bf4_to_f4(u32x2 w) { return (f32x4){__uint_as_float(w.x << 16), __uint_as_float(w.x & 0xffff0000u), __uint_as_float(w.y << 16), __uint_as_float(w.y & 0xffff0000u)}; }
; DI void post_rwkv_phase(const PZ& p, int wave, int lane) {
;     ...
;             const f32x4 y = bf4_to_f4(__builtin_nontemporal_load((const u32x2*)(HA + (size_t)m * 1024) + lane + 64 * j)) + bf4_to_f4(__builtin_nontemporal_load((const u32x2*)(YB + (size_t)m * 1024) + lane + 64 * j));
;             const float mu = red16(y.x + y.y + y.z + y.w) * (1.f / 64.f);
;             const f32x4 d = y - mu;
;             const float var = red16(d.x * d.x + d.y * d.y + d.z * d.z + d.w * d.w) * (1.f / 64.f);
;             const float rstd = rsqrtf(var + 64e-5f);
.Lprw_nopf:
	v_add_f32_e32 v189, v110, v111
	v_add_f32_e32 v190, v114, v115
	v_add_f32_e32 v191, v118, v119
	v_add_f32_e32 v192, v122, v123
	v_add_f32_e32 v189, v112, v189
	v_add_f32_e32 v190, v116, v190
	v_add_f32_e32 v191, v120, v191
	v_add_f32_e32 v192, v124, v192
	v_add_f32_e32 v189, v113, v189
	v_add_f32_e32 v190, v117, v190
	v_add_f32_e32 v191, v121, v191
	v_add_f32_e32 v192, v125, v192
	v_add_f32_dpp v189, v189, v189 quad_perm:[1,0,3,2] row_mask:0xf bank_mask:0xf bound_ctrl:1
	v_add_f32_dpp v190, v190, v190 quad_perm:[1,0,3,2] row_mask:0xf bank_mask:0xf bound_ctrl:1
	v_add_f32_dpp v191, v191, v191 quad_perm:[1,0,3,2] row_mask:0xf bank_mask:0xf bound_ctrl:1
	v_add_f32_dpp v192, v192, v192 quad_perm:[1,0,3,2] row_mask:0xf bank_mask:0xf bound_ctrl:1
	v_add_f32_dpp v189, v189, v189 quad_perm:[2,3,0,1] row_mask:0xf bank_mask:0xf bound_ctrl:1
	v_add_f32_dpp v190, v190, v190 quad_perm:[2,3,0,1] row_mask:0xf bank_mask:0xf bound_ctrl:1
	v_add_f32_dpp v191, v191, v191 quad_perm:[2,3,0,1] row_mask:0xf bank_mask:0xf bound_ctrl:1
	v_add_f32_dpp v192, v192, v192 quad_perm:[2,3,0,1] row_mask:0xf bank_mask:0xf bound_ctrl:1
	v_add_f32_dpp v189, v189, v189 row_half_mirror row_mask:0xf bank_mask:0xf bound_ctrl:1
	v_add_f32_dpp v190, v190, v190 row_half_mirror row_mask:0xf bank_mask:0xf bound_ctrl:1
	v_add_f32_dpp v191, v191, v191 row_half_mirror row_mask:0xf bank_mask:0xf bound_ctrl:1
	v_add_f32_dpp v192, v192, v192 row_half_mirror row_mask:0xf bank_mask:0xf bound_ctrl:1
	v_add_f32_dpp v189, v189, v189 row_mirror row_mask:0xf bank_mask:0xf bound_ctrl:1
	v_add_f32_dpp v190, v190, v190 row_mirror row_mask:0xf bank_mask:0xf bound_ctrl:1
	v_add_f32_dpp v191, v191, v191 row_mirror row_mask:0xf bank_mask:0xf bound_ctrl:1
	v_add_f32_dpp v192, v192, v192 row_mirror row_mask:0xf bank_mask:0xf bound_ctrl:1
	v_fmac_f32_e32 v110, 0xbc800000, v189
	v_fmac_f32_e32 v114, 0xbc800000, v190
	v_fmac_f32_e32 v118, 0xbc800000, v191
	v_fmac_f32_e32 v122, 0xbc800000, v192
	v_fmac_f32_e32 v111, 0xbc800000, v189
	v_fmac_f32_e32 v115, 0xbc800000, v190
	v_fmac_f32_e32 v119, 0xbc800000, v191
	v_fmac_f32_e32 v123, 0xbc800000, v192
	v_fmac_f32_e32 v112, 0xbc800000, v189
	v_fmac_f32_e32 v116, 0xbc800000, v190
	v_fmac_f32_e32 v120, 0xbc800000, v191
	v_fmac_f32_e32 v124, 0xbc800000, v192
	v_fmac_f32_e32 v113, 0xbc800000, v189
	v_fmac_f32_e32 v117, 0xbc800000, v190
	v_fmac_f32_e32 v121, 0xbc800000, v191
	v_fmac_f32_e32 v125, 0xbc800000, v192
	v_mul_f32_e32 v193, v110, v110
	v_mul_f32_e32 v194, v114, v114
	v_mul_f32_e32 v195, v118, v118
	v_mul_f32_e32 v196, v122, v122
	v_fmac_f32_e32 v193, v111, v111
	v_fmac_f32_e32 v194, v115, v115
	v_fmac_f32_e32 v195, v119, v119
	v_fmac_f32_e32 v196, v123, v123
	v_fmac_f32_e32 v193, v112, v112
	v_fmac_f32_e32 v194, v116, v116
	v_fmac_f32_e32 v195, v120, v120
	v_fmac_f32_e32 v196, v124, v124
	v_fmac_f32_e32 v193, v113, v113
	v_fmac_f32_e32 v194, v117, v117
	v_fmac_f32_e32 v195, v121, v121
	v_fmac_f32_e32 v196, v125, v125
	v_add_f32_dpp v193, v193, v193 quad_perm:[1,0,3,2] row_mask:0xf bank_mask:0xf bound_ctrl:1
	v_add_f32_dpp v194, v194, v194 quad_perm:[1,0,3,2] row_mask:0xf bank_mask:0xf bound_ctrl:1
	v_add_f32_dpp v195, v195, v195 quad_perm:[1,0,3,2] row_mask:0xf bank_mask:0xf bound_ctrl:1
	v_add_f32_dpp v196, v196, v196 quad_perm:[1,0,3,2] row_mask:0xf bank_mask:0xf bound_ctrl:1
	v_add_f32_dpp v193, v193, v193 quad_perm:[2,3,0,1] row_mask:0xf bank_mask:0xf bound_ctrl:1
	v_add_f32_dpp v194, v194, v194 quad_perm:[2,3,0,1] row_mask:0xf bank_mask:0xf bound_ctrl:1
	v_add_f32_dpp v195, v195, v195 quad_perm:[2,3,0,1] row_mask:0xf bank_mask:0xf bound_ctrl:1
; DI float red16(float v) { v += DPPF(v, 0xB1); v += DPPF(v, 0x4E); v += DPPF(v, 0x141); v += DPPF(v, 0x140); return v; }
; DI f32x4 bf4_to_f4(u32x2 w) { return (f32x4){__uint_as_float(w.x << 16), __uint_as_float(w.x & 0xffff0000u), __uint_as_float(w.y << 16), __uint_as_float(w.y & 0xffff0000u)}; }
; DI u32x2 f4_to_bf4(f32x4 v) { return (u32x2){pk2(v.x, v.y), pk2(v.z, v.w)}; }
; DI void post_rwkv_phase(const PZ& p, int wave, int lane) {
;     ...
;             const float var = red16(d.x * d.x + d.y * d.y + d.z * d.z + d.w * d.w) * (1.f / 64.f);
;             const float rstd = rsqrtf(var + 64e-5f);
;             const f32x4 lw = *((const f32x4*)p.in(34) + lane + 64 * j), lb = *((const f32x4*)p.in(35) + lane + 64 * j);
;             const float bon = 0.5f * (BS[(size_t)m * 16 + head] + BS[((size_t)MTOK + m) * 16 + head]);
;             const f32x4 v = bf4_to_f4(__builtin_nontemporal_load((const u32x2*)(rkv + (size_t)m * 3072 + 2048) + lane + 64 * j));
;             const f32x4 gg = bf4_to_f4(__builtin_nontemporal_load((const u32x2*)(rkv + (size_t)m * 3072) + lane + 64 * j));
;             outv[j] = (d * rstd * lw + lb + v * bon) * gg;
;         }
; #pragma unroll
;         for (int j = 0; j < 4; ++j) *((u32x2*)(HA + (size_t)m * 1024) + lane + 64 * j) = f4_to_bf4(outv[j]);
	v_add_f32_dpp v196, v196, v196 quad_perm:[2,3,0,1] row_mask:0xf bank_mask:0xf bound_ctrl:1
	v_add_f32_dpp v193, v193, v193 row_half_mirror row_mask:0xf bank_mask:0xf bound_ctrl:1
	v_add_f32_dpp v194, v194, v194 row_half_mirror row_mask:0xf bank_mask:0xf bound_ctrl:1
	v_add_f32_dpp v195, v195, v195 row_half_mirror row_mask:0xf bank_mask:0xf bound_ctrl:1
	v_add_f32_dpp v196, v196, v196 row_half_mirror row_mask:0xf bank_mask:0xf bound_ctrl:1
	v_add_f32_dpp v193, v193, v193 row_mirror row_mask:0xf bank_mask:0xf bound_ctrl:1
	v_add_f32_dpp v194, v194, v194 row_mirror row_mask:0xf bank_mask:0xf bound_ctrl:1
	v_add_f32_dpp v195, v195, v195 row_mirror row_mask:0xf bank_mask:0xf bound_ctrl:1
	v_add_f32_dpp v196, v196, v196 row_mirror row_mask:0xf bank_mask:0xf bound_ctrl:1
	v_fmaak_f32 v193, v107, v193, 0x3a27c5ac
	v_fmaak_f32 v194, v107, v194, 0x3a27c5ac
	v_fmaak_f32 v195, v107, v195, 0x3a27c5ac
	v_fmaak_f32 v196, v107, v196, 0x3a27c5ac
	v_rsq_f32_e32 v212, v193
	v_rsq_f32_e32 v213, v194
	v_rsq_f32_e32 v214, v195
	v_rsq_f32_e32 v215, v196
	v_mul_f32_e32 v110, v110, v212
	v_mul_f32_e32 v114, v114, v213
	v_mul_f32_e32 v118, v118, v214
	v_mul_f32_e32 v122, v122, v215
	v_mul_f32_e32 v111, v111, v212
	v_mul_f32_e32 v115, v115, v213
	v_mul_f32_e32 v119, v119, v214
	v_mul_f32_e32 v123, v123, v215
	v_mul_f32_e32 v112, v112, v212
	v_mul_f32_e32 v116, v116, v213
	v_mul_f32_e32 v120, v120, v214
	v_mul_f32_e32 v124, v124, v215
	v_mul_f32_e32 v113, v113, v212
	v_mul_f32_e32 v117, v117, v213
	v_mul_f32_e32 v121, v121, v214
	v_mul_f32_e32 v125, v125, v215
	v_fma_f32 v110, v70, v110, v86
	v_fma_f32 v114, v74, v114, v90
	v_fma_f32 v118, v78, v118, v94
	v_fma_f32 v122, v82, v122, v98
	v_fma_f32 v111, v71, v111, v87
	v_fma_f32 v115, v75, v115, v91
	v_fma_f32 v119, v79, v119, v95
	v_fma_f32 v123, v83, v123, v99
	v_fma_f32 v112, v72, v112, v88
	v_fma_f32 v116, v76, v116, v92
	v_fma_f32 v120, v80, v120, v96
	v_fma_f32 v124, v84, v124, v100
	v_fma_f32 v113, v73, v113, v89
	v_fma_f32 v117, v77, v117, v93
	v_fma_f32 v121, v81, v121, v97
	v_fma_f32 v125, v85, v125, v101
	v_fmac_f32_e32 v110, v185, v126
	v_fmac_f32_e32 v114, v186, v130
	v_fmac_f32_e32 v118, v187, v134
	v_fmac_f32_e32 v122, v188, v138
	v_fmac_f32_e32 v111, v185, v127
	v_fmac_f32_e32 v115, v186, v131
	v_fmac_f32_e32 v119, v187, v135
	v_fmac_f32_e32 v123, v188, v139
	v_fmac_f32_e32 v112, v185, v128
	v_fmac_f32_e32 v116, v186, v132
	v_fmac_f32_e32 v120, v187, v136
	v_fmac_f32_e32 v124, v188, v140
	v_fmac_f32_e32 v113, v185, v129
	v_fmac_f32_e32 v117, v186, v133
	v_fmac_f32_e32 v121, v187, v137
	v_fmac_f32_e32 v125, v188, v141
	v_mul_f32_e32 v110, v110, v169
	v_mul_f32_e32 v114, v114, v173
	v_mul_f32_e32 v118, v118, v177
	v_mul_f32_e32 v122, v122, v181
	v_mul_f32_e32 v111, v111, v170
	v_mul_f32_e32 v115, v115, v174
	v_mul_f32_e32 v119, v119, v178
	v_mul_f32_e32 v123, v123, v182
	v_mul_f32_e32 v112, v112, v171
	v_mul_f32_e32 v116, v116, v175
	v_mul_f32_e32 v120, v120, v179
	v_mul_f32_e32 v124, v124, v183
	v_mul_f32_e32 v113, v113, v172
	v_mul_f32_e32 v117, v117, v176
	v_mul_f32_e32 v121, v121, v180
	v_mul_f32_e32 v125, v125, v184
	v_cvt_pk_bf16_f32 v216, v110, v111
	v_cvt_pk_bf16_f32 v217, v112, v113
	v_cvt_pk_bf16_f32 v218, v114, v115
	v_cvt_pk_bf16_f32 v219, v116, v117
	v_cvt_pk_bf16_f32 v220, v118, v119
	v_cvt_pk_bf16_f32 v221, v120, v121
	v_cvt_pk_bf16_f32 v222, v122, v123
	v_cvt_pk_bf16_f32 v223, v124, v125
	global_store_dwordx2 v[60:61], v[216:217], off offset:0
	global_store_dwordx2 v[60:61], v[218:219], off offset:512
	global_store_dwordx2 v[60:61], v[220:221], off offset:1024
	global_store_dwordx2 v[60:61], v[222:223], off offset:1536
	s_cbranch_scc0 .Lprw_loop
